# v52 plus all individually validated edits stacked: simple transposes 32 loads in flight, up row-stat hoist, memory-attention Q prefetch, final-norm stat loads batched
# speedup vs baseline: 1.0065x; 1.0050x over previous
.LBB0_1356:
	v_readlane_b32 s76, v255, 37
	v_readlane_b32 s77, v255, 38
	buffer_inv sc1
	s_mov_b64 s[18:19], -1
	v_lshl_add_u64 v[8:9], v[142:143], 2, s[76:77]
	global_load_dwordx4 v[4:7], v[8:9], off offset:16
	global_load_dwordx4 v[12:15], v[8:9], off
	global_load_dwordx4 v[0:3], v[8:9], off offset:528
	s_nop 0
	global_load_dwordx4 v[8:11], v[8:9], off offset:512
	s_nop 0
	global_load_dword v206, v[114:115], off sc1
	global_load_dword v207, v[114:115], off offset:64 sc1
	global_load_dword v208, v[114:115], off offset:128 sc1
	global_load_dword v209, v[114:115], off offset:192 sc1
	global_load_dword v210, v[114:115], off offset:512 sc1
	global_load_dword v211, v[114:115], off offset:576 sc1
	global_load_dword v212, v[114:115], off offset:640 sc1
	global_load_dword v213, v[114:115], off offset:704 sc1
	v_readlane_b32 s78, v255, 39
	v_readlane_b32 s79, v255, 40
	s_waitcnt vmcnt(7) lgkmcnt(0)
	v_mov_b32_e32 v142, v206
	v_fmamk_f32 v142, v142, 0x3a000000, v194
	v_mul_f32_e32 v143, 0x4b800000, v142
	v_cmp_gt_f32_e32 vcc, s38, v142
	s_nop 1
	v_cndmask_b32_e32 v142, v142, v143, vcc
	v_rsq_f32_e32 v142, v142
	s_nop 0
	v_mul_f32_e32 v143, 0x45800000, v142
	v_cndmask_b32_e32 v142, v142, v143, vcc
	v_pk_mul_f32 v[126:127], v[126:127], v[142:143] op_sel_hi:[1,0]
	v_pk_mul_f32 v[128:129], v[128:129], v[142:143] op_sel_hi:[1,0]
	v_pk_mul_f32 v[192:193], v[122:123], v[142:143] op_sel_hi:[1,0]
	v_pk_mul_f32 v[122:123], v[124:125], v[142:143] op_sel_hi:[1,0]
	v_pk_mul_f32 v[124:125], v[144:145], v[142:143] op_sel_hi:[1,0]
	v_pk_mul_f32 v[144:145], v[120:121], v[142:143] op_sel_hi:[1,0]
	v_pk_mul_f32 v[196:197], v[118:119], v[142:143] op_sel_hi:[1,0]
	v_pk_mul_f32 v[142:143], v[116:117], v[142:143] op_sel_hi:[1,0]
	v_pk_mul_f32 v[118:119], v[14:15], v[128:129]
	v_pk_mul_f32 v[116:117], v[12:13], v[126:127]
	v_pk_mul_f32 v[122:123], v[6:7], v[122:123]
	v_pk_mul_f32 v[120:121], v[4:5], v[192:193]
	v_pk_mul_f32 v[126:127], v[10:11], v[144:145]
	v_pk_mul_f32 v[124:125], v[8:9], v[124:125]
	v_pk_mul_f32 v[144:145], v[2:3], v[142:143]
	v_pk_mul_f32 v[142:143], v[0:1], v[196:197]
	global_store_dwordx4 v[140:141], v[116:119], off
	global_store_dwordx4 v[140:141], v[120:123], off offset:16
	global_store_dwordx4 v[140:141], v[124:127], off offset:512
	global_store_dwordx4 v[140:141], v[142:145], off offset:528
	s_nop 1
	s_waitcnt vmcnt(10) lgkmcnt(0)
	v_mov_b32_e32 v116, v207
	v_fmamk_f32 v116, v116, 0x3a000000, v194
	v_mul_f32_e32 v117, 0x4b800000, v116
	v_cmp_gt_f32_e32 vcc, s38, v116
	s_nop 1
	v_cndmask_b32_e32 v116, v116, v117, vcc
	v_rsq_f32_e32 v116, v116
	s_nop 0
	v_mul_f32_e32 v117, 0x45800000, v116
	v_cndmask_b32_e32 v116, v116, v117, vcc
	v_pk_mul_f32 v[110:111], v[110:111], v[116:117] op_sel_hi:[1,0]
	v_pk_mul_f32 v[112:113], v[112:113], v[116:117] op_sel_hi:[1,0]
	v_pk_mul_f32 v[106:107], v[106:107], v[116:117] op_sel_hi:[1,0]
	v_pk_mul_f32 v[108:109], v[108:109], v[116:117] op_sel_hi:[1,0]
	v_pk_mul_f32 v[118:119], v[102:103], v[116:117] op_sel_hi:[1,0]
	v_pk_mul_f32 v[120:121], v[104:105], v[116:117] op_sel_hi:[1,0]
	v_pk_mul_f32 v[122:123], v[98:99], v[116:117] op_sel_hi:[1,0]
	v_pk_mul_f32 v[116:117], v[100:101], v[116:117] op_sel_hi:[1,0]
	v_pk_mul_f32 v[100:101], v[14:15], v[112:113]
	v_pk_mul_f32 v[98:99], v[12:13], v[110:111]
	v_pk_mul_f32 v[104:105], v[6:7], v[108:109]
	v_pk_mul_f32 v[102:103], v[4:5], v[106:107]
	v_pk_mul_f32 v[108:109], v[10:11], v[120:121]
	v_pk_mul_f32 v[106:107], v[8:9], v[118:119]
	v_pk_mul_f32 v[112:113], v[2:3], v[116:117]
	v_pk_mul_f32 v[110:111], v[0:1], v[122:123]
	global_store_dwordx4 v[146:147], v[98:101], off
	global_store_dwordx4 v[146:147], v[102:105], off offset:16
	global_store_dwordx4 v[146:147], v[106:109], off offset:512
	global_store_dwordx4 v[146:147], v[110:113], off offset:528
	s_nop 1
	s_waitcnt vmcnt(13) lgkmcnt(0)
	v_mov_b32_e32 v98, v208
	v_fmamk_f32 v98, v98, 0x3a000000, v194
	v_mul_f32_e32 v99, 0x4b800000, v98
	v_cmp_gt_f32_e32 vcc, s38, v98
	s_nop 1
	v_cndmask_b32_e32 v98, v98, v99, vcc
	v_rsq_f32_e32 v98, v98
	s_nop 0
	v_mul_f32_e32 v99, 0x45800000, v98
	v_cndmask_b32_e32 v98, v98, v99, vcc
	v_pk_mul_f32 v[92:93], v[92:93], v[98:99] op_sel_hi:[1,0]
	v_pk_mul_f32 v[94:95], v[94:95], v[98:99] op_sel_hi:[1,0]
	v_pk_mul_f32 v[88:89], v[88:89], v[98:99] op_sel_hi:[1,0]
	v_pk_mul_f32 v[90:91], v[90:91], v[98:99] op_sel_hi:[1,0]
	v_pk_mul_f32 v[100:101], v[84:85], v[98:99] op_sel_hi:[1,0]
	v_pk_mul_f32 v[102:103], v[86:87], v[98:99] op_sel_hi:[1,0]
	v_pk_mul_f32 v[104:105], v[80:81], v[98:99] op_sel_hi:[1,0]
	v_pk_mul_f32 v[98:99], v[82:83], v[98:99] op_sel_hi:[1,0]
	v_pk_mul_f32 v[82:83], v[14:15], v[94:95]
	v_pk_mul_f32 v[80:81], v[12:13], v[92:93]
	v_pk_mul_f32 v[86:87], v[6:7], v[90:91]
	v_pk_mul_f32 v[84:85], v[4:5], v[88:89]
	v_pk_mul_f32 v[90:91], v[10:11], v[102:103]
	v_pk_mul_f32 v[88:89], v[8:9], v[100:101]
	v_pk_mul_f32 v[94:95], v[2:3], v[98:99]
	v_pk_mul_f32 v[92:93], v[0:1], v[104:105]
	global_store_dwordx4 v[148:149], v[80:83], off
	global_store_dwordx4 v[148:149], v[84:87], off offset:16
	global_store_dwordx4 v[148:149], v[88:91], off offset:512
	global_store_dwordx4 v[148:149], v[92:95], off offset:528
	s_nop 1
	s_waitcnt vmcnt(16) lgkmcnt(0)
	v_mov_b32_e32 v80, v209
	v_fmamk_f32 v80, v80, 0x3a000000, v194
	v_mul_f32_e32 v81, 0x4b800000, v80
	v_cmp_gt_f32_e32 vcc, s38, v80
	s_nop 1
	v_cndmask_b32_e32 v80, v80, v81, vcc
	v_rsq_f32_e32 v80, v80
	s_nop 0
	v_mul_f32_e32 v81, 0x45800000, v80
	v_cndmask_b32_e32 v80, v80, v81, vcc
	v_pk_mul_f32 v[76:77], v[76:77], v[80:81] op_sel_hi:[1,0]
	v_pk_mul_f32 v[78:79], v[78:79], v[80:81] op_sel_hi:[1,0]
	v_pk_mul_f32 v[72:73], v[72:73], v[80:81] op_sel_hi:[1,0]
	v_pk_mul_f32 v[74:75], v[74:75], v[80:81] op_sel_hi:[1,0]
	v_pk_mul_f32 v[82:83], v[68:69], v[80:81] op_sel_hi:[1,0]
	v_pk_mul_f32 v[84:85], v[70:71], v[80:81] op_sel_hi:[1,0]
	v_pk_mul_f32 v[86:87], v[64:65], v[80:81] op_sel_hi:[1,0]
	v_pk_mul_f32 v[80:81], v[66:67], v[80:81] op_sel_hi:[1,0]
	v_pk_mul_f32 v[66:67], v[14:15], v[78:79]
	v_pk_mul_f32 v[64:65], v[12:13], v[76:77]
	v_pk_mul_f32 v[70:71], v[6:7], v[74:75]
	v_pk_mul_f32 v[68:69], v[4:5], v[72:73]
	v_pk_mul_f32 v[74:75], v[10:11], v[84:85]
	v_pk_mul_f32 v[72:73], v[8:9], v[82:83]
	v_pk_mul_f32 v[78:79], v[2:3], v[80:81]
	v_pk_mul_f32 v[76:77], v[0:1], v[86:87]
	global_store_dwordx4 v[154:155], v[64:67], off
	global_store_dwordx4 v[154:155], v[68:71], off offset:16
	global_store_dwordx4 v[154:155], v[72:75], off offset:512
	global_store_dwordx4 v[154:155], v[76:79], off offset:528
	s_nop 1
	s_waitcnt vmcnt(19) lgkmcnt(0)
	v_mov_b32_e32 v64, v210
	v_fmamk_f32 v64, v64, 0x3a000000, v194
	v_mul_f32_e32 v65, 0x4b800000, v64
	v_cmp_gt_f32_e32 vcc, s38, v64
	s_nop 1
	v_cndmask_b32_e32 v64, v64, v65, vcc
	v_rsq_f32_e32 v64, v64
	s_nop 0
	v_mul_f32_e32 v65, 0x45800000, v64
	v_cndmask_b32_e32 v64, v64, v65, vcc
	v_pk_mul_f32 v[60:61], v[60:61], v[64:65] op_sel_hi:[1,0]
	v_pk_mul_f32 v[62:63], v[62:63], v[64:65] op_sel_hi:[1,0]
	v_pk_mul_f32 v[56:57], v[56:57], v[64:65] op_sel_hi:[1,0]
	v_pk_mul_f32 v[58:59], v[58:59], v[64:65] op_sel_hi:[1,0]
	v_pk_mul_f32 v[66:67], v[52:53], v[64:65] op_sel_hi:[1,0]
	v_pk_mul_f32 v[68:69], v[54:55], v[64:65] op_sel_hi:[1,0]
	v_pk_mul_f32 v[70:71], v[48:49], v[64:65] op_sel_hi:[1,0]
	v_pk_mul_f32 v[64:65], v[50:51], v[64:65] op_sel_hi:[1,0]
	v_pk_mul_f32 v[50:51], v[14:15], v[62:63]
	v_pk_mul_f32 v[48:49], v[12:13], v[60:61]
	v_pk_mul_f32 v[54:55], v[6:7], v[58:59]
	v_pk_mul_f32 v[52:53], v[4:5], v[56:57]
	v_pk_mul_f32 v[58:59], v[10:11], v[68:69]
	v_pk_mul_f32 v[56:57], v[8:9], v[66:67]
	v_pk_mul_f32 v[62:63], v[2:3], v[64:65]
	v_pk_mul_f32 v[60:61], v[0:1], v[70:71]
	global_store_dwordx4 v[168:169], v[48:51], off
	global_store_dwordx4 v[168:169], v[52:55], off offset:16
	global_store_dwordx4 v[168:169], v[56:59], off offset:512
	global_store_dwordx4 v[168:169], v[60:63], off offset:528
	s_nop 1
	s_waitcnt vmcnt(22) lgkmcnt(0)
	v_mov_b32_e32 v48, v211
	v_fmamk_f32 v48, v48, 0x3a000000, v194
	v_mul_f32_e32 v49, 0x4b800000, v48
	v_cmp_gt_f32_e32 vcc, s38, v48
	s_nop 1
	v_cndmask_b32_e32 v48, v48, v49, vcc
	v_rsq_f32_e32 v48, v48
	s_nop 0
	v_mul_f32_e32 v49, 0x45800000, v48
	v_cndmask_b32_e32 v48, v48, v49, vcc
	v_pk_mul_f32 v[44:45], v[44:45], v[48:49] op_sel_hi:[1,0]
	v_pk_mul_f32 v[46:47], v[46:47], v[48:49] op_sel_hi:[1,0]
	v_pk_mul_f32 v[40:41], v[40:41], v[48:49] op_sel_hi:[1,0]
	v_pk_mul_f32 v[42:43], v[42:43], v[48:49] op_sel_hi:[1,0]
	v_pk_mul_f32 v[50:51], v[36:37], v[48:49] op_sel_hi:[1,0]
	v_pk_mul_f32 v[52:53], v[38:39], v[48:49] op_sel_hi:[1,0]
	v_pk_mul_f32 v[54:55], v[32:33], v[48:49] op_sel_hi:[1,0]
	v_pk_mul_f32 v[48:49], v[34:35], v[48:49] op_sel_hi:[1,0]
	v_pk_mul_f32 v[34:35], v[14:15], v[46:47]
	v_pk_mul_f32 v[32:33], v[12:13], v[44:45]
	v_pk_mul_f32 v[38:39], v[6:7], v[42:43]
	v_pk_mul_f32 v[36:37], v[4:5], v[40:41]
	v_pk_mul_f32 v[42:43], v[10:11], v[52:53]
	v_pk_mul_f32 v[40:41], v[8:9], v[50:51]
	v_pk_mul_f32 v[46:47], v[2:3], v[48:49]
	v_pk_mul_f32 v[44:45], v[0:1], v[54:55]
	global_store_dwordx4 v[172:173], v[32:35], off
	global_store_dwordx4 v[172:173], v[36:39], off offset:16
	global_store_dwordx4 v[172:173], v[40:43], off offset:512
	global_store_dwordx4 v[172:173], v[44:47], off offset:528
	s_nop 1
	s_waitcnt vmcnt(25) lgkmcnt(0)
	v_mov_b32_e32 v32, v212
	v_fmamk_f32 v32, v32, 0x3a000000, v194
	v_mul_f32_e32 v33, 0x4b800000, v32
	v_cmp_gt_f32_e32 vcc, s38, v32
	s_nop 1
	v_cndmask_b32_e32 v32, v32, v33, vcc
	v_rsq_f32_e32 v32, v32
	s_nop 0
	v_mul_f32_e32 v33, 0x45800000, v32
	v_cndmask_b32_e32 v32, v32, v33, vcc
	v_pk_mul_f32 v[28:29], v[28:29], v[32:33] op_sel_hi:[1,0]
	v_pk_mul_f32 v[30:31], v[30:31], v[32:33] op_sel_hi:[1,0]
	v_pk_mul_f32 v[24:25], v[24:25], v[32:33] op_sel_hi:[1,0]
	v_pk_mul_f32 v[26:27], v[26:27], v[32:33] op_sel_hi:[1,0]
	v_pk_mul_f32 v[34:35], v[20:21], v[32:33] op_sel_hi:[1,0]
	v_pk_mul_f32 v[36:37], v[22:23], v[32:33] op_sel_hi:[1,0]
	v_pk_mul_f32 v[38:39], v[16:17], v[32:33] op_sel_hi:[1,0]
	v_pk_mul_f32 v[32:33], v[18:19], v[32:33] op_sel_hi:[1,0]
	v_pk_mul_f32 v[18:19], v[14:15], v[30:31]
	v_pk_mul_f32 v[16:17], v[12:13], v[28:29]
	v_pk_mul_f32 v[22:23], v[6:7], v[26:27]
	v_pk_mul_f32 v[20:21], v[4:5], v[24:25]
	v_pk_mul_f32 v[26:27], v[10:11], v[36:37]
	v_pk_mul_f32 v[24:25], v[8:9], v[34:35]
	v_pk_mul_f32 v[30:31], v[2:3], v[32:33]
	v_pk_mul_f32 v[28:29], v[0:1], v[38:39]
	global_store_dwordx4 v[174:175], v[16:19], off
	global_store_dwordx4 v[174:175], v[20:23], off offset:16
	global_store_dwordx4 v[174:175], v[24:27], off offset:512
	global_store_dwordx4 v[174:175], v[28:31], off offset:528
	s_nop 1
	s_andn2_b64 vcc, exec, s[36:37]
	s_waitcnt vmcnt(28) lgkmcnt(0)
	v_mov_b32_e32 v16, v213
	v_fmamk_f32 v16, v16, 0x3a000000, v194
	v_mul_f32_e32 v17, 0x4b800000, v16
	v_cmp_gt_f32_e64 s[42:43], s38, v16
	s_nop 1
	v_cndmask_b32_e64 v16, v16, v17, s[42:43]
	v_rsq_f32_e32 v16, v16
	s_nop 0
	v_mul_f32_e32 v17, 0x45800000, v16
	v_cndmask_b32_e64 v16, v16, v17, s[42:43]
	v_pk_mul_f32 v[18:19], v[182:183], v[16:17] op_sel_hi:[1,0]
	v_pk_mul_f32 v[20:21], v[178:179], v[16:17] op_sel_hi:[1,0]
	v_pk_mul_f32 v[22:23], v[180:181], v[16:17] op_sel_hi:[1,0]
	v_pk_mul_f32 v[24:25], v[176:177], v[16:17] op_sel_hi:[1,0]
	v_pk_mul_f32 v[26:27], v[186:187], v[16:17] op_sel_hi:[1,0]
	v_pk_mul_f32 v[28:29], v[184:185], v[16:17] op_sel_hi:[1,0]
	v_pk_mul_f32 v[30:31], v[190:191], v[16:17] op_sel_hi:[1,0]
	v_pk_mul_f32 v[16:17], v[188:189], v[16:17] op_sel_hi:[1,0]
	v_pk_mul_f32 v[14:15], v[14:15], v[20:21]
	v_pk_mul_f32 v[12:13], v[12:13], v[18:19]
	v_pk_mul_f32 v[6:7], v[6:7], v[24:25]
	v_pk_mul_f32 v[4:5], v[4:5], v[22:23]
	v_pk_mul_f32 v[10:11], v[10:11], v[28:29]
	v_pk_mul_f32 v[8:9], v[8:9], v[26:27]
	v_pk_mul_f32 v[2:3], v[2:3], v[16:17]
	v_pk_mul_f32 v[0:1], v[0:1], v[30:31]
	global_store_dwordx4 v[152:153], v[12:15], off
	global_store_dwordx4 v[152:153], v[4:7], off offset:16
	global_store_dwordx4 v[152:153], v[8:11], off offset:512
	global_store_dwordx4 v[152:153], v[0:3], off offset:528
	s_cbranch_vccnz .LBB0_1319
	s_andn2_b64 vcc, exec, s[12:13]
	s_cbranch_vccnz .LBB0_1318
	s_barrier
	s_branch .LBB0_1318
